# diff-attn deferral split: carried half gets only its exps in the QK phase (in place); its row-sum adds and bf16 packs ride in the first 8 PV gaps
# speedup vs baseline: 1.0033x; 1.0024x over previous
; #define LAS __attribute__((address_space(3)))
; #define DMA_GROUP(t_) do { const int kt_ = ((t_) + 3 < NT) ? (t_) + 3 : NT - 1; int vt_ = ((t_) + 2 < NT) ? (t_) + 2 : NT - 1; vt_ = vt_ < 0 ? 0 : vt_; DMA_K(kt_, ((t_) + 3) & 3); DMA_V(vt_, ((t_) + 2) & 3); } while (0)
; template <bool FIXM> __device__ __forceinline__ void diff_unit(int b, int h, int qb, float lam, const bf16* U, const bf16* VTa, bf16* Y, const float* subg, const float* qgain, const int* pos, unsigned char* lds, int tid, int wid, int lane) {
;     ...
;         DMA_GROUP(-3); DMA_GROUP(-2); DMA_GROUP(-1);
;         asm volatile("s_waitcnt vmcnt(6)" ::: "memory");
;         __builtin_amdgcn_s_barrier();
;         float m = -INFINITY, l = 0.f;
; #pragma unroll
;         for (int db = 0; db < 4; ++db) o[db] = f32x16{};
;         u32x4 pwA[4], pwB[4];
; #pragma unroll
;         for (int i = 0; i < 4; ++i) { pwA[i] = u32x4{0u, 0u, 0u, 0u}; pwB[i] = pwA[i]; }
;         const LAS unsigned char* kfp = (const LAS unsigned char*)lds + prow * 128; const LAS unsigned char* vfp = (const LAS unsigned char*)lds + 4 * DK_BYTES + r32 * 128;
;         unsigned kofs[4], vofs[4];
; #pragma unroll
;         for (int k4 = 0; k4 < 4; ++k4) { kofs[k4] = ((2 * k4 + hi) ^ ((prow >> 1) & 7)) * 16; vofs[k4] = ((2 * k4 + hi) ^ ((r32 >> 1) & 7)) * 16; }
.LBB0_385:
	s_add_i32 s93, s76, -4
	s_add_i32 s92, s72, s76
	s_add_i32 s0, s76, -1
	s_cmp_lt_u32 s0, s82
	s_cselect_b32 s78, s0, s33
	s_add_i32 s91, s76, -2
	s_cmp_lt_u32 s91, s82
	s_cselect_b32 s84, s91, s33
	s_mul_i32 s98, s78, 0x58000
	s_add_u32 s98, s100, s98
	s_addc_u32 s99, s101, 0
	s_and_b32 s0, s77, 0x6000
	s_add_i32 m0, s67, s0
	s_lshl_b64 s[0:1], s[84:85], 7
	s_add_u32 s0, s74, s0
	s_addc_u32 s1, s75, s1
	global_load_lds_dwordx4 v202, s[98:99]
	s_add_i32 s98, s2, 0xc000
	s_and_b32 s98, s98, 0xc000
	s_add_i32 s98, s67, s98
	s_add_i32 m0, s98, 0x8000
	s_nop 0
	global_load_lds_dwordx4 v204, s[0:1]
	s_add_i32 m0, s98, 0xa000
	s_add_u32 s0, s0, 0x400000
	s_addc_u32 s1, s1, 0
	global_load_lds_dwordx4 v204, s[0:1]
	s_and_b32 s0, s2, 0xc000
	s_cmp_le_u32 s93, s83
	v_add_u32_e32 v243, s0, v230
	s_cselect_b64 s[96:97], -1, 0
	s_cmp_gt_u32 s93, s83
	s_mov_b64 s[0:1], -1
	s_cbranch_scc1 .LBB0_389
	s_cmp_eq_u32 s93, 1
	s_cbranch_scc1 .Lmy_oddqk_first
	s_add_i32 s0, s77, 0xffffa000
	s_and_b32 s0, s0, 0x6000
	v_add_u32_e32 v244, s0, v229
	v_add_u32_e32 v245, v244, v232
	ds_read_b128 v[2:5], v245
	ds_read_b128 v[10:13], v241
	ds_read_b128 v[6:9], v245 offset:4096
	v_add_u32_e32 v245, v244, v234
	ds_read_b128 v[18:21], v245
	ds_read_b128 v[14:17], v241 offset:1024
	ds_read_b128 v[22:25], v245 offset:4096
	v_add_u32_e32 v245, v244, v236
	ds_read_b128 v[26:29], v245
	ds_read_b128 v[34:37], v241 offset:2048
	ds_read_b128 v[30:33], v245 offset:4096
	v_add_u32_e32 v245, v244, v238
	ds_read_b128 v[38:41], v245
	ds_read_b128 v[46:49], v241 offset:3072
	ds_read_b128 v[42:45], v245 offset:4096
	s_waitcnt lgkmcnt(10)
	v_mfma_f32_32x32x16_bf16 v[146:161], v[2:5], v[10:13], 0
	v_exp_f32_e32 v50, v50
	v_exp_f32_e32 v51, v51
	s_waitcnt lgkmcnt(9)
	v_mfma_f32_32x32x16_bf16 v[130:145], v[6:9], v[10:13], 0
	v_exp_f32_e32 v52, v52
	v_exp_f32_e32 v53, v53
	s_waitcnt lgkmcnt(7)
	v_mfma_f32_32x32x16_bf16 v[146:161], v[18:21], v[14:17], v[146:161]
	v_exp_f32_e32 v54, v54
	v_exp_f32_e32 v55, v55
	s_waitcnt lgkmcnt(6)
	v_mfma_f32_32x32x16_bf16 v[130:145], v[22:25], v[14:17], v[130:145]
	v_exp_f32_e32 v56, v56
	v_exp_f32_e32 v57, v57
	s_waitcnt lgkmcnt(4)
	v_mfma_f32_32x32x16_bf16 v[146:161], v[26:29], v[34:37], v[146:161]
	v_exp_f32_e32 v58, v58
	v_exp_f32_e32 v59, v59
	s_waitcnt lgkmcnt(3)
	v_mfma_f32_32x32x16_bf16 v[130:145], v[30:33], v[34:37], v[130:145]
	v_exp_f32_e32 v60, v60
	v_exp_f32_e32 v61, v61
	s_waitcnt lgkmcnt(1)
	v_mfma_f32_32x32x16_bf16 v[146:161], v[38:41], v[46:49], v[146:161]
	v_exp_f32_e32 v62, v62
	v_exp_f32_e32 v63, v63
	s_waitcnt lgkmcnt(0)
	v_mfma_f32_32x32x16_bf16 v[130:145], v[42:45], v[46:49], v[130:145]
	v_exp_f32_e32 v64, v64
	v_exp_f32_e32 v65, v65
	s_branch .Lmy_oddqk_join

.LBB0_388:
	s_cmp_eq_u32 s93, 1
	s_cbranch_scc1 .Lmy_oddpv_first
	v_add_u32_e32 v18, v243, v233
	v_add_u32_e32 v19, v243, v235
	v_add_u32_e32 v20, v243, v237
	v_add_u32_e32 v21, v243, v239
	ds_read_b128 v[2:5], v18 offset:32768
	ds_read_b128 v[6:9], v18 offset:36864
	ds_read_b128 v[10:13], v18 offset:40960
	s_nop 5
	v_exp_f32_e32 v22, v146
	s_waitcnt lgkmcnt(2)
	v_mfma_f32_32x32x16_bf16 v[114:129], v[2:5], v[162:165], v[114:129]
	ds_read_b128 v[14:17], v18 offset:45056
	v_add_f32_e32 v242, v50, v242
	v_add_f32_e32 v242, v51, v242
	v_cvt_pk_bf16_f32 v170, v50, v51
	v_exp_f32_e32 v23, v147
	s_waitcnt lgkmcnt(2)
	v_mfma_f32_32x32x16_bf16 v[98:113], v[6:9], v[162:165], v[98:113]
	ds_read_b128 v[2:5], v19 offset:32768
	v_add_f32_e32 v242, v52, v242
	v_add_f32_e32 v242, v53, v242
	v_cvt_pk_bf16_f32 v171, v52, v53
	v_add_f32_e32 v24, v22, v23
	v_cvt_pk_bf16_f32 v178, v22, v23
	v_exp_f32_e32 v22, v148
	s_waitcnt lgkmcnt(2)
	v_mfma_f32_32x32x16_bf16 v[82:97], v[10:13], v[162:165], v[82:97]
	ds_read_b128 v[6:9], v19 offset:36864
	v_add_f32_e32 v242, v54, v242
	v_add_f32_e32 v242, v55, v242
	v_cvt_pk_bf16_f32 v172, v54, v55
	v_exp_f32_e32 v23, v149
	s_waitcnt lgkmcnt(2)
	v_mfma_f32_32x32x16_bf16 v[66:81], v[14:17], v[162:165], v[66:81]
	ds_read_b128 v[10:13], v19 offset:40960
	v_add_f32_e32 v242, v56, v242
	v_add_f32_e32 v242, v57, v242
	v_cvt_pk_bf16_f32 v173, v56, v57
	v_add_f32_e32 v24, v22, v24
	v_add_f32_e32 v24, v23, v24
	v_cvt_pk_bf16_f32 v179, v22, v23
	v_exp_f32_e32 v22, v150
	s_waitcnt lgkmcnt(2)
	v_mfma_f32_32x32x16_bf16 v[114:129], v[2:5], v[166:169], v[114:129]
	ds_read_b128 v[14:17], v19 offset:45056
	v_add_f32_e32 v242, v58, v242
	v_add_f32_e32 v242, v59, v242
	v_cvt_pk_bf16_f32 v174, v58, v59
	v_exp_f32_e32 v23, v151
	s_waitcnt lgkmcnt(2)
	v_mfma_f32_32x32x16_bf16 v[98:113], v[6:9], v[166:169], v[98:113]
	ds_read_b128 v[2:5], v20 offset:32768
	v_add_f32_e32 v242, v60, v242
	v_add_f32_e32 v242, v61, v242
	v_cvt_pk_bf16_f32 v175, v60, v61
	v_add_f32_e32 v24, v22, v24
	v_add_f32_e32 v24, v23, v24
	v_cvt_pk_bf16_f32 v180, v22, v23
	v_exp_f32_e32 v22, v152
	s_waitcnt lgkmcnt(2)
	v_mfma_f32_32x32x16_bf16 v[82:97], v[10:13], v[166:169], v[82:97]
	ds_read_b128 v[6:9], v20 offset:36864
	v_add_f32_e32 v242, v62, v242
	v_add_f32_e32 v242, v63, v242
	v_cvt_pk_bf16_f32 v176, v62, v63
	v_exp_f32_e32 v23, v153
	s_waitcnt lgkmcnt(2)
	v_mfma_f32_32x32x16_bf16 v[66:81], v[14:17], v[166:169], v[66:81]
	ds_read_b128 v[10:13], v20 offset:40960
	v_add_f32_e32 v242, v64, v242
	v_add_f32_e32 v242, v65, v242
	v_cvt_pk_bf16_f32 v177, v64, v65
	v_add_f32_e32 v24, v22, v24
	v_add_f32_e32 v24, v23, v24
	v_cvt_pk_bf16_f32 v181, v22, v23
	v_exp_f32_e32 v22, v154
	s_waitcnt lgkmcnt(2)
	v_mfma_f32_32x32x16_bf16 v[114:129], v[2:5], v[170:173], v[114:129]
	ds_read_b128 v[14:17], v20 offset:45056
	v_exp_f32_e32 v23, v155
	s_waitcnt lgkmcnt(2)
	v_mfma_f32_32x32x16_bf16 v[98:113], v[6:9], v[170:173], v[98:113]
	ds_read_b128 v[2:5], v21 offset:32768
	v_add_f32_e32 v24, v22, v24
	v_add_f32_e32 v24, v23, v24
	v_cvt_pk_bf16_f32 v146, v22, v23
	v_exp_f32_e32 v22, v156
	s_waitcnt lgkmcnt(2)
	v_mfma_f32_32x32x16_bf16 v[82:97], v[10:13], v[170:173], v[82:97]
	ds_read_b128 v[6:9], v21 offset:36864
	v_exp_f32_e32 v23, v157
	s_waitcnt lgkmcnt(2)
	v_mfma_f32_32x32x16_bf16 v[66:81], v[14:17], v[170:173], v[66:81]
	ds_read_b128 v[10:13], v21 offset:40960
	v_add_f32_e32 v24, v22, v24
	v_add_f32_e32 v24, v23, v24
	v_cvt_pk_bf16_f32 v147, v22, v23
	v_exp_f32_e32 v22, v158
	s_waitcnt lgkmcnt(2)
	v_mfma_f32_32x32x16_bf16 v[114:129], v[2:5], v[174:177], v[114:129]
	ds_read_b128 v[14:17], v21 offset:45056
	v_exp_f32_e32 v23, v159
	s_waitcnt lgkmcnt(2)
	v_mfma_f32_32x32x16_bf16 v[98:113], v[6:9], v[174:177], v[98:113]
	v_add_f32_e32 v24, v22, v24
	v_add_f32_e32 v24, v23, v24
	v_cvt_pk_bf16_f32 v148, v22, v23
	v_exp_f32_e32 v22, v160
	s_waitcnt lgkmcnt(1)
	v_mfma_f32_32x32x16_bf16 v[82:97], v[10:13], v[174:177], v[82:97]
	v_exp_f32_e32 v23, v161
	s_waitcnt lgkmcnt(0)
	v_mfma_f32_32x32x16_bf16 v[66:81], v[14:17], v[174:177], v[66:81]
	v_add_f32_e32 v24, v22, v24
	v_add_f32_e32 v24, v23, v24
	v_cvt_pk_bf16_f32 v149, v22, v23
	v_add_f32_e32 v0, v242, v24
	s_branch .Lmy_oddpv_join
.Lmy_oddpv_first:
	v_add_u32_e32 v18, v243, v233
	v_add_u32_e32 v19, v243, v235
	v_add_u32_e32 v20, v243, v237
	v_add_u32_e32 v21, v243, v239
	ds_read_b128 v[2:5], v18 offset:32768
	ds_read_b128 v[6:9], v18 offset:36864
	ds_read_b128 v[10:13], v18 offset:40960
	s_nop 5
	v_exp_f32_e32 v22, v146
	s_waitcnt lgkmcnt(2)
	v_mfma_f32_32x32x16_bf16 v[114:129], v[2:5], v[162:165], v[114:129]
	ds_read_b128 v[14:17], v18 offset:45056
	v_exp_f32_e32 v23, v147
	s_waitcnt lgkmcnt(2)
	v_mfma_f32_32x32x16_bf16 v[98:113], v[6:9], v[162:165], v[98:113]
	ds_read_b128 v[2:5], v19 offset:32768
	v_add_f32_e32 v24, v22, v23
	v_cvt_pk_bf16_f32 v178, v22, v23
	v_exp_f32_e32 v22, v148
	s_waitcnt lgkmcnt(2)
	v_mfma_f32_32x32x16_bf16 v[82:97], v[10:13], v[162:165], v[82:97]
	ds_read_b128 v[6:9], v19 offset:36864
	v_exp_f32_e32 v23, v149
	s_waitcnt lgkmcnt(2)
	v_mfma_f32_32x32x16_bf16 v[66:81], v[14:17], v[162:165], v[66:81]
	ds_read_b128 v[10:13], v19 offset:40960
	v_add_f32_e32 v24, v22, v24
	v_add_f32_e32 v24, v23, v24
	v_cvt_pk_bf16_f32 v179, v22, v23
	v_exp_f32_e32 v22, v150
	s_waitcnt lgkmcnt(2)
	v_mfma_f32_32x32x16_bf16 v[114:129], v[2:5], v[166:169], v[114:129]
	ds_read_b128 v[14:17], v19 offset:45056
	v_exp_f32_e32 v23, v151
	s_waitcnt lgkmcnt(2)
	v_mfma_f32_32x32x16_bf16 v[98:113], v[6:9], v[166:169], v[98:113]
	ds_read_b128 v[2:5], v20 offset:32768
	v_add_f32_e32 v24, v22, v24
	v_add_f32_e32 v24, v23, v24
	v_cvt_pk_bf16_f32 v180, v22, v23
	v_exp_f32_e32 v22, v152
	s_waitcnt lgkmcnt(2)
	v_mfma_f32_32x32x16_bf16 v[82:97], v[10:13], v[166:169], v[82:97]
	ds_read_b128 v[6:9], v20 offset:36864
	v_exp_f32_e32 v23, v153
	s_waitcnt lgkmcnt(2)
	v_mfma_f32_32x32x16_bf16 v[66:81], v[14:17], v[166:169], v[66:81]
	ds_read_b128 v[10:13], v20 offset:40960
	v_add_f32_e32 v24, v22, v24
	v_add_f32_e32 v24, v23, v24
	v_cvt_pk_bf16_f32 v181, v22, v23
	v_exp_f32_e32 v22, v154
	s_waitcnt lgkmcnt(2)
	v_mfma_f32_32x32x16_bf16 v[114:129], v[2:5], v[170:173], v[114:129]
	ds_read_b128 v[14:17], v20 offset:45056
	v_exp_f32_e32 v23, v155
	s_waitcnt lgkmcnt(2)
	v_mfma_f32_32x32x16_bf16 v[98:113], v[6:9], v[170:173], v[98:113]
	ds_read_b128 v[2:5], v21 offset:32768
	v_add_f32_e32 v24, v22, v24
	v_add_f32_e32 v24, v23, v24
	v_cvt_pk_bf16_f32 v146, v22, v23
	v_exp_f32_e32 v22, v156
	s_waitcnt lgkmcnt(2)
	v_mfma_f32_32x32x16_bf16 v[82:97], v[10:13], v[170:173], v[82:97]
	ds_read_b128 v[6:9], v21 offset:36864
	v_exp_f32_e32 v23, v157
	s_waitcnt lgkmcnt(2)
	v_mfma_f32_32x32x16_bf16 v[66:81], v[14:17], v[170:173], v[66:81]
	ds_read_b128 v[10:13], v21 offset:40960
	v_add_f32_e32 v24, v22, v24
	v_add_f32_e32 v24, v23, v24
	v_cvt_pk_bf16_f32 v147, v22, v23
	v_exp_f32_e32 v22, v158
	s_waitcnt lgkmcnt(2)
	v_mfma_f32_32x32x16_bf16 v[114:129], v[2:5], v[174:177], v[114:129]
	ds_read_b128 v[14:17], v21 offset:45056
	v_exp_f32_e32 v23, v159
	s_waitcnt lgkmcnt(2)
	v_mfma_f32_32x32x16_bf16 v[98:113], v[6:9], v[174:177], v[98:113]
	v_add_f32_e32 v24, v22, v24
	v_add_f32_e32 v24, v23, v24
	v_cvt_pk_bf16_f32 v148, v22, v23
	v_exp_f32_e32 v22, v160
	s_waitcnt lgkmcnt(1)
	v_mfma_f32_32x32x16_bf16 v[82:97], v[10:13], v[174:177], v[82:97]
	v_exp_f32_e32 v23, v161
	s_waitcnt lgkmcnt(0)
	v_mfma_f32_32x32x16_bf16 v[66:81], v[14:17], v[174:177], v[66:81]
	v_add_f32_e32 v24, v22, v24
	v_add_f32_e32 v24, v23, v24
	v_cvt_pk_bf16_f32 v149, v22, v23
	v_add_f32_e32 v0, v242, v24
.Lmy_oddpv_join:
	s_mov_b64 s[0:1], 0
.LBB0_389:
	s_and_b64 vcc, exec, s[0:1]
	s_cbranch_vccz .LBB0_393
	s_add_i32 s0, s76, -5
	s_cmp_gt_u32 s0, s83
	s_cbranch_scc1 .LBB0_392
	s_cmp_eq_u32 s93, 1
	s_cbranch_scc1 .Lmy_odddrain_skip
	v_exp_f32_e32 v246, v50
	v_exp_f32_e32 v247, v51
	v_add_f32_e32 v242, v246, v242
	v_add_f32_e32 v242, v247, v242
	v_cvt_pk_bf16_f32 v170, v246, v247
	v_exp_f32_e32 v246, v52
	v_exp_f32_e32 v247, v53
	v_add_f32_e32 v242, v246, v242
	v_add_f32_e32 v242, v247, v242
	v_cvt_pk_bf16_f32 v171, v246, v247
	v_exp_f32_e32 v246, v54
	v_exp_f32_e32 v247, v55
	v_add_f32_e32 v242, v246, v242
	v_add_f32_e32 v242, v247, v242
	v_cvt_pk_bf16_f32 v172, v246, v247
	v_exp_f32_e32 v246, v56
	v_exp_f32_e32 v247, v57
	v_add_f32_e32 v242, v246, v242
	v_add_f32_e32 v242, v247, v242
	v_cvt_pk_bf16_f32 v173, v246, v247
	v_exp_f32_e32 v246, v58
	v_exp_f32_e32 v247, v59
	v_add_f32_e32 v242, v246, v242
	v_add_f32_e32 v242, v247, v242
	v_cvt_pk_bf16_f32 v174, v246, v247
	v_exp_f32_e32 v246, v60
	v_exp_f32_e32 v247, v61
	v_add_f32_e32 v242, v246, v242
	v_add_f32_e32 v242, v247, v242
	v_cvt_pk_bf16_f32 v175, v246, v247
	v_exp_f32_e32 v246, v62
	v_exp_f32_e32 v247, v63
	v_add_f32_e32 v242, v246, v242
	v_add_f32_e32 v242, v247, v242
	v_cvt_pk_bf16_f32 v176, v246, v247
	v_exp_f32_e32 v246, v64
	v_exp_f32_e32 v247, v65
	v_add_f32_e32 v242, v246, v242
	v_add_f32_e32 v242, v247, v242
	v_cvt_pk_bf16_f32 v177, v246, v247

.LBB0_398:
	s_andn2_b64 vcc, exec, s[0:1]
	s_cbranch_vccnz .LBB0_403
	s_add_i32 s0, s77, 0xffffc000
	s_and_b32 s0, s0, 0x6000
	v_add_u32_e32 v244, s0, v229
	v_add_u32_e32 v245, v244, v232
	ds_read_b128 v[2:5], v245
	ds_read_b128 v[162:165], v241
	ds_read_b128 v[6:9], v245 offset:4096
	v_add_u32_e32 v245, v244, v234
	ds_read_b128 v[10:13], v245
	ds_read_b128 v[166:169], v241 offset:1024
	ds_read_b128 v[14:17], v245 offset:4096
	v_add_u32_e32 v245, v244, v236
	ds_read_b128 v[18:21], v245
	ds_read_b128 v[170:173], v241 offset:2048
	ds_read_b128 v[22:25], v245 offset:4096
	v_add_u32_e32 v245, v244, v238
	ds_read_b128 v[26:29], v245
	ds_read_b128 v[174:177], v241 offset:3072
	ds_read_b128 v[30:33], v245 offset:4096
	s_waitcnt lgkmcnt(10)
	v_mfma_f32_32x32x16_bf16 v[34:49], v[2:5], v[162:165], 0
	v_exp_f32_e32 v130, v130
	v_exp_f32_e32 v131, v131
	s_waitcnt lgkmcnt(9)
	v_mfma_f32_32x32x16_bf16 v[50:65], v[6:9], v[162:165], 0
	v_exp_f32_e32 v132, v132
	v_exp_f32_e32 v133, v133
	s_waitcnt lgkmcnt(7)
	v_mfma_f32_32x32x16_bf16 v[34:49], v[10:13], v[166:169], v[34:49]
	v_exp_f32_e32 v134, v134
	v_exp_f32_e32 v135, v135
	s_waitcnt lgkmcnt(6)
	v_mfma_f32_32x32x16_bf16 v[50:65], v[14:17], v[166:169], v[50:65]
	v_exp_f32_e32 v136, v136
	v_exp_f32_e32 v137, v137
	s_waitcnt lgkmcnt(4)
	v_mfma_f32_32x32x16_bf16 v[34:49], v[18:21], v[170:173], v[34:49]
	v_exp_f32_e32 v138, v138
	v_exp_f32_e32 v139, v139
	s_waitcnt lgkmcnt(3)
	v_mfma_f32_32x32x16_bf16 v[50:65], v[22:25], v[170:173], v[50:65]
	v_exp_f32_e32 v140, v140
	v_exp_f32_e32 v141, v141
	s_waitcnt lgkmcnt(1)
	v_mfma_f32_32x32x16_bf16 v[34:49], v[26:29], v[174:177], v[34:49]
	v_exp_f32_e32 v142, v142
	v_exp_f32_e32 v143, v143
	s_waitcnt lgkmcnt(0)
	v_mfma_f32_32x32x16_bf16 v[50:65], v[30:33], v[174:177], v[50:65]
	v_exp_f32_e32 v144, v144
	v_exp_f32_e32 v145, v145
	s_cmp_lg_u32 s92, 3
	s_cbranch_scc1 .LBB0_401
	v_mov_b32_e32 v18, v240
	s_nop 0
	v_cmp_gt_i32_e64 s[62:63], 22, v18
	v_cmp_gt_i32_e64 s[64:65], 23, v18
	v_cmp_gt_i32_e64 s[60:61], 21, v18
	s_and_b64 s[62:63], s[64:65], s[62:63]
	v_cmp_gt_i32_e64 s[58:59], 20, v18
	s_and_b64 s[60:61], s[62:63], s[60:61]
	v_cmp_gt_i32_e64 s[56:57], 19, v18
	s_and_b64 s[58:59], s[60:61], s[58:59]
	v_cmp_gt_i32_e64 s[54:55], 18, v18
	s_and_b64 s[56:57], s[58:59], s[56:57]
	v_cmp_gt_i32_e64 s[52:53], 17, v18
	s_and_b64 s[54:55], s[56:57], s[54:55]
	v_cmp_gt_i32_e64 s[50:51], 16, v18
	s_and_b64 s[52:53], s[54:55], s[52:53]
	v_cmp_gt_i32_e64 s[48:49], 7, v18
	s_and_b64 s[50:51], s[52:53], s[50:51]
	v_cmp_gt_i32_e64 s[46:47], 6, v18
	s_and_b64 s[48:49], s[50:51], s[48:49]
	v_cmp_gt_i32_e64 s[44:45], 5, v18
	s_and_b64 s[46:47], s[48:49], s[46:47]
	v_cmp_gt_i32_e64 s[42:43], 4, v18
	s_and_b64 s[44:45], s[46:47], s[44:45]
	v_cmp_gt_i32_e64 s[40:41], 3, v18
	s_and_b64 s[42:43], s[44:45], s[42:43]
	v_cmp_gt_i32_e64 s[38:39], 2, v18
	s_and_b64 s[40:41], s[42:43], s[40:41]
	v_cmp_gt_i32_e64 s[36:37], 1, v18
	s_and_b64 s[38:39], s[40:41], s[38:39]
	v_cmp_gt_i32_e64 s[34:35], 0, v18
	s_and_b64 s[36:37], s[38:39], s[36:37]
	s_and_b64 s[34:35], s[36:37], s[34:35]
	v_cmp_gt_i32_e64 s[30:31], 54, v18
	v_cndmask_b32_e64 v34, v34, v227, s[34:35]
	v_cmp_gt_i32_e64 s[34:35], 55, v18
	v_cmp_gt_i32_e64 s[28:29], 53, v18
	s_and_b64 s[30:31], s[34:35], s[30:31]
	v_cmp_gt_i32_e64 s[26:27], 52, v18
	s_and_b64 s[28:29], s[30:31], s[28:29]
	v_cmp_gt_i32_e64 s[24:25], 51, v18
	s_and_b64 s[26:27], s[28:29], s[26:27]
	v_cmp_gt_i32_e64 s[22:23], 50, v18
	s_and_b64 s[24:25], s[26:27], s[24:25]
	v_cmp_gt_i32_e64 s[20:21], 49, v18
	s_and_b64 s[22:23], s[24:25], s[22:23]
	v_cmp_gt_i32_e64 s[18:19], 48, v18
	s_and_b64 s[20:21], s[22:23], s[20:21]
	v_cmp_gt_i32_e64 s[16:17], 39, v18
	s_and_b64 s[18:19], s[20:21], s[18:19]
	v_cmp_gt_i32_e64 s[14:15], 38, v18
	s_and_b64 s[16:17], s[18:19], s[16:17]
	v_cmp_gt_i32_e64 s[12:13], 37, v18
	s_and_b64 s[14:15], s[16:17], s[14:15]
	v_cmp_gt_i32_e64 s[10:11], 36, v18
	s_and_b64 s[12:13], s[14:15], s[12:13]
	v_cmp_gt_i32_e64 s[8:9], 35, v18
	s_and_b64 s[10:11], s[12:13], s[10:11]
	v_cmp_gt_i32_e64 s[6:7], 34, v18
	s_and_b64 s[8:9], s[10:11], s[8:9]
	v_cmp_gt_i32_e64 s[0:1], 33, v18
	s_and_b64 s[6:7], s[8:9], s[6:7]
	v_cmp_gt_i32_e32 vcc, 32, v18
	s_and_b64 s[0:1], s[6:7], s[0:1]
	s_and_b64 vcc, s[0:1], vcc
	v_cndmask_b32_e64 v49, v49, v227, s[64:65]
	v_cndmask_b32_e64 v48, v48, v227, s[62:63]
	v_cndmask_b32_e64 v47, v47, v227, s[60:61]
	v_cndmask_b32_e64 v46, v46, v227, s[58:59]
	v_cndmask_b32_e64 v45, v45, v227, s[56:57]
	v_cndmask_b32_e64 v44, v44, v227, s[54:55]
	v_cndmask_b32_e64 v43, v43, v227, s[52:53]
	v_cndmask_b32_e64 v42, v42, v227, s[50:51]
	v_cndmask_b32_e64 v41, v41, v227, s[48:49]
	v_cndmask_b32_e64 v40, v40, v227, s[46:47]
	v_cndmask_b32_e64 v39, v39, v227, s[44:45]
	v_cndmask_b32_e64 v38, v38, v227, s[42:43]
	v_cndmask_b32_e64 v37, v37, v227, s[40:41]
	v_cndmask_b32_e64 v36, v36, v227, s[38:39]
	v_cndmask_b32_e64 v35, v35, v227, s[36:37]
	v_cndmask_b32_e64 v65, v65, v227, s[34:35]
	v_cndmask_b32_e64 v64, v64, v227, s[30:31]
	v_cndmask_b32_e64 v63, v63, v227, s[28:29]
	v_cndmask_b32_e64 v62, v62, v227, s[26:27]
	v_cndmask_b32_e64 v61, v61, v227, s[24:25]
	v_cndmask_b32_e64 v60, v60, v227, s[22:23]
	v_cndmask_b32_e64 v59, v59, v227, s[20:21]
	v_cndmask_b32_e64 v58, v58, v227, s[18:19]
	v_cndmask_b32_e64 v57, v57, v227, s[16:17]
	v_cndmask_b32_e64 v56, v56, v227, s[14:15]
	v_cndmask_b32_e64 v55, v55, v227, s[12:13]
	v_cndmask_b32_e64 v54, v54, v227, s[10:11]
	v_cndmask_b32_e64 v53, v53, v227, s[8:9]
	v_cndmask_b32_e64 v52, v52, v227, s[6:7]
	v_cndmask_b32_e64 v51, v51, v227, s[0:1]
	v_cndmask_b32_e32 v50, v50, v227, vcc
.LBB0_401:
	v_add_u32_e32 v18, v248, v233
	v_add_u32_e32 v19, v248, v235
	v_add_u32_e32 v20, v248, v237
	v_add_u32_e32 v21, v248, v239
	ds_read_b128 v[2:5], v18 offset:32768
	ds_read_b128 v[6:9], v18 offset:36864
	ds_read_b128 v[10:13], v18 offset:40960
	s_nop 5
	v_exp_f32_e32 v22, v34
	s_waitcnt lgkmcnt(2)
	v_mfma_f32_32x32x16_bf16 v[114:129], v[2:5], v[178:181], v[114:129]
	ds_read_b128 v[14:17], v18 offset:45056
	v_add_f32_e32 v0, v130, v0
	v_add_f32_e32 v0, v131, v0
	v_cvt_pk_bf16_f32 v150, v130, v131
	v_exp_f32_e32 v23, v35
	s_waitcnt lgkmcnt(2)
	v_mfma_f32_32x32x16_bf16 v[98:113], v[6:9], v[178:181], v[98:113]
	ds_read_b128 v[2:5], v19 offset:32768
	v_add_f32_e32 v0, v132, v0
	v_add_f32_e32 v0, v133, v0
	v_cvt_pk_bf16_f32 v151, v132, v133
	v_add_f32_e32 v24, v22, v23
	v_cvt_pk_bf16_f32 v162, v22, v23
	v_exp_f32_e32 v22, v36
	s_waitcnt lgkmcnt(2)
	v_mfma_f32_32x32x16_bf16 v[82:97], v[10:13], v[178:181], v[82:97]
	ds_read_b128 v[6:9], v19 offset:36864
	v_add_f32_e32 v0, v134, v0
	v_add_f32_e32 v0, v135, v0
	v_cvt_pk_bf16_f32 v152, v134, v135
	v_exp_f32_e32 v23, v37
	s_waitcnt lgkmcnt(2)
	v_mfma_f32_32x32x16_bf16 v[66:81], v[14:17], v[178:181], v[66:81]
	ds_read_b128 v[10:13], v19 offset:40960
	v_add_f32_e32 v0, v136, v0
	v_add_f32_e32 v0, v137, v0
	v_cvt_pk_bf16_f32 v153, v136, v137
	v_add_f32_e32 v24, v22, v24
	v_add_f32_e32 v24, v23, v24
	v_cvt_pk_bf16_f32 v163, v22, v23
	v_exp_f32_e32 v22, v38
	s_waitcnt lgkmcnt(2)
	v_mfma_f32_32x32x16_bf16 v[114:129], v[2:5], v[146:149], v[114:129]
	ds_read_b128 v[14:17], v19 offset:45056
	v_add_f32_e32 v0, v138, v0
	v_add_f32_e32 v0, v139, v0
	v_cvt_pk_bf16_f32 v130, v138, v139
	v_exp_f32_e32 v23, v39
	s_waitcnt lgkmcnt(2)
	v_mfma_f32_32x32x16_bf16 v[98:113], v[6:9], v[146:149], v[98:113]
	ds_read_b128 v[2:5], v20 offset:32768
	v_add_f32_e32 v0, v140, v0
	v_add_f32_e32 v0, v141, v0
	v_cvt_pk_bf16_f32 v131, v140, v141
	v_add_f32_e32 v24, v22, v24
	v_add_f32_e32 v24, v23, v24
	v_cvt_pk_bf16_f32 v164, v22, v23
	v_exp_f32_e32 v22, v40
	s_waitcnt lgkmcnt(2)
	v_mfma_f32_32x32x16_bf16 v[82:97], v[10:13], v[146:149], v[82:97]
	ds_read_b128 v[6:9], v20 offset:36864
	v_add_f32_e32 v0, v142, v0
	v_add_f32_e32 v0, v143, v0
	v_cvt_pk_bf16_f32 v132, v142, v143
	v_exp_f32_e32 v23, v41
	s_waitcnt lgkmcnt(2)
	v_mfma_f32_32x32x16_bf16 v[66:81], v[14:17], v[146:149], v[66:81]
	ds_read_b128 v[10:13], v20 offset:40960
	v_add_f32_e32 v0, v144, v0
	v_add_f32_e32 v0, v145, v0
	v_cvt_pk_bf16_f32 v133, v144, v145
	v_add_f32_e32 v24, v22, v24
	v_add_f32_e32 v24, v23, v24
	v_cvt_pk_bf16_f32 v165, v22, v23
	v_exp_f32_e32 v22, v42
	s_waitcnt lgkmcnt(2)
	v_mfma_f32_32x32x16_bf16 v[114:129], v[2:5], v[150:153], v[114:129]
	ds_read_b128 v[14:17], v20 offset:45056
	v_exp_f32_e32 v23, v43
	s_waitcnt lgkmcnt(2)
	v_mfma_f32_32x32x16_bf16 v[98:113], v[6:9], v[150:153], v[98:113]
	ds_read_b128 v[2:5], v21 offset:32768
	v_add_f32_e32 v24, v22, v24
	v_add_f32_e32 v24, v23, v24
	v_cvt_pk_bf16_f32 v166, v22, v23
	v_exp_f32_e32 v22, v44
	s_waitcnt lgkmcnt(2)
	v_mfma_f32_32x32x16_bf16 v[82:97], v[10:13], v[150:153], v[82:97]
	ds_read_b128 v[6:9], v21 offset:36864
	v_exp_f32_e32 v23, v45
	s_waitcnt lgkmcnt(2)
	v_mfma_f32_32x32x16_bf16 v[66:81], v[14:17], v[150:153], v[66:81]
	ds_read_b128 v[10:13], v21 offset:40960
	v_add_f32_e32 v24, v22, v24
	v_add_f32_e32 v24, v23, v24
	v_cvt_pk_bf16_f32 v167, v22, v23
	v_exp_f32_e32 v22, v46
	s_waitcnt lgkmcnt(2)
	v_mfma_f32_32x32x16_bf16 v[114:129], v[2:5], v[130:133], v[114:129]
	ds_read_b128 v[14:17], v21 offset:45056
	v_exp_f32_e32 v23, v47
	s_waitcnt lgkmcnt(2)
	v_mfma_f32_32x32x16_bf16 v[98:113], v[6:9], v[130:133], v[98:113]
	v_add_f32_e32 v24, v22, v24
	v_add_f32_e32 v24, v23, v24
	v_cvt_pk_bf16_f32 v168, v22, v23
	v_exp_f32_e32 v22, v48
	s_waitcnt lgkmcnt(1)
	v_mfma_f32_32x32x16_bf16 v[82:97], v[10:13], v[130:133], v[82:97]
	v_exp_f32_e32 v23, v49
	s_waitcnt lgkmcnt(0)
	v_mfma_f32_32x32x16_bf16 v[66:81], v[14:17], v[130:133], v[66:81]
	v_add_f32_e32 v24, v22, v24
	v_add_f32_e32 v24, v23, v24
	v_cvt_pk_bf16_f32 v169, v22, v23
	v_add_f32_e32 v242, v0, v24
	s_branch .LBB0_404
